# attention FAST loop edges: last K-fragment read pair issued one MFMA gap earlier (wait recounted 8->10), scalar bookkeeping moved in front of the two step barriers
# speedup vs baseline: 1.0192x; 1.0045x over previous
.LBB0_413:
	s_mov_b32 s16, s26
	s_mov_b32 s2, s18
	s_mov_b32 s3, s24
	v_lshl_add_u32 v69, s17, 1, v232
	ds_read_b64_tr_b16 v[76:77], v69 offset:24576
	ds_read_b64_tr_b16 v[78:79], v69 offset:25088
	v_add_f32_e32 v72, v100, v101
	v_add_f32_e32 v72, v102, v72
	v_add_f32_e32 v72, v103, v72
	v_add_f32_e32 v72, v104, v72
	v_add_f32_e32 v72, v105, v72
	v_cvt_pk_bf16_f32 v160, v100, v101
	v_cvt_pk_bf16_f32 v161, v102, v103
	s_waitcnt lgkmcnt(9)
	v_mfma_f32_32x32x16_bf16 v[132:147], v[208:211], v[176:179], 0
	v_add_f32_e32 v72, v106, v72
	v_add_f32_e32 v72, v107, v72
	v_add_f32_e32 v72, v108, v72
	v_add_f32_e32 v72, v109, v72
	v_cvt_pk_bf16_f32 v162, v104, v105
	v_cvt_pk_bf16_f32 v163, v106, v107
	s_waitcnt lgkmcnt(8)
	v_mfma_f32_32x32x16_bf16 v[116:131], v[200:203], v[176:179], 0
	ds_read_b64_tr_b16 v[80:81], v69 offset:25600
	ds_read_b64_tr_b16 v[82:83], v69 offset:26112
	v_add_f32_e32 v72, v110, v72
	v_add_f32_e32 v72, v111, v72
	v_add_f32_e32 v72, v112, v72
	v_add_f32_e32 v72, v113, v72
	v_cvt_pk_bf16_f32 v156, v108, v109
	v_cvt_pk_bf16_f32 v157, v110, v111
	s_waitcnt lgkmcnt(9)
	v_mfma_f32_32x32x16_bf16 v[132:147], v[204:207], v[172:175], v[132:147]
	v_add_f32_e32 v72, v114, v72
	v_add_f32_e32 v72, v115, v72
	v_add_f32_e32 v72, v84, v72
	v_add_f32_e32 v72, v85, v72
	v_cvt_pk_bf16_f32 v158, v112, v113
	v_cvt_pk_bf16_f32 v159, v114, v115
	s_waitcnt lgkmcnt(8)
	v_mfma_f32_32x32x16_bf16 v[116:131], v[196:199], v[172:175], v[116:131]
	ds_read_b64_tr_b16 v[100:101], v69 offset:26624
	ds_read_b64_tr_b16 v[102:103], v69 offset:27136
	v_add_f32_e32 v72, v86, v72
	v_add_f32_e32 v72, v87, v72
	v_add_f32_e32 v72, v88, v72
	v_add_f32_e32 v72, v89, v72
	v_cvt_pk_bf16_f32 v152, v84, v85
	v_cvt_pk_bf16_f32 v153, v86, v87
	s_waitcnt lgkmcnt(9)
	v_mfma_f32_32x32x16_bf16 v[132:147], v[192:195], v[168:171], v[132:147]
	v_add_f32_e32 v72, v90, v72
	v_add_f32_e32 v72, v91, v72
	v_add_f32_e32 v72, v92, v72
	v_add_f32_e32 v72, v93, v72
	v_cvt_pk_bf16_f32 v154, v88, v89
	v_cvt_pk_bf16_f32 v155, v90, v91
	s_waitcnt lgkmcnt(8)
	v_mfma_f32_32x32x16_bf16 v[116:131], v[188:191], v[168:171], v[116:131]
	ds_read_b64_tr_b16 v[84:85], v69 offset:27648
	ds_read_b64_tr_b16 v[86:87], v69 offset:28160
	v_add_f32_e32 v72, v94, v72
	v_add_f32_e32 v72, v95, v72
	v_add_f32_e32 v72, v96, v72
	v_add_f32_e32 v72, v97, v72
	v_cvt_pk_bf16_f32 v148, v92, v93
	v_cvt_pk_bf16_f32 v149, v94, v95
	s_waitcnt lgkmcnt(9)
	v_mfma_f32_32x32x16_bf16 v[132:147], v[184:187], v[164:167], v[132:147]
	v_add_f32_e32 v72, v98, v72
	v_add_f32_e32 v72, v99, v72
	v_add_f32_e32 v72, 0, v72
	v_cvt_pk_bf16_f32 v150, v96, v97
	v_cvt_pk_bf16_f32 v151, v98, v99
	s_waitcnt lgkmcnt(8)
	v_mfma_f32_32x32x16_bf16 v[116:131], v[180:183], v[164:167], v[116:131]
	v_lshl_add_u64 v[74:75], v[0:1], 0, s[14:15]
	v_add_f32_e32 v68, v68, v72
	s_add_i32 m0, s24, s0
	v_lshl_add_u64 v[72:73], v[74:75], 0, s[76:77]
	global_load_lds_dwordx4 v[72:73], off
	s_lshl_b32 s17, s26, 1
	s_add_i32 s17, s17, s1
	s_mov_b32 m0, s17
	v_lshl_add_u64 v[72:73], v[70:71], 0, s[14:15]
	v_lshl_add_u64 v[88:89], v[72:73], 0, s[90:91]
	global_load_lds_dwordx4 v[88:89], off
	s_add_i32 m0, s17, 0x2000
	v_lshl_add_u64 v[88:89], v[72:73], 0, s[92:93]
	global_load_lds_dwordx4 v[88:89], off
	s_waitcnt lgkmcnt(6)
	v_mfma_f32_32x32x16_bf16 v[36:51], v[160:163], v[76:79], v[36:51]
	v_exp_f32_e32 v132, v132
	v_exp_f32_e32 v133, v133
	ds_read_b64_tr_b16 v[76:77], v69 offset:28672
	ds_read_b64_tr_b16 v[78:79], v69 offset:29184
	s_waitcnt lgkmcnt(6)
	v_mfma_f32_32x32x16_bf16 v[36:51], v[156:159], v[80:83], v[36:51]
	v_exp_f32_e32 v134, v134
	v_exp_f32_e32 v135, v135
	ds_read_b64_tr_b16 v[80:81], v69 offset:29696
	ds_read_b64_tr_b16 v[82:83], v69 offset:30208
	s_waitcnt lgkmcnt(6)
	v_mfma_f32_32x32x16_bf16 v[36:51], v[152:155], v[100:103], v[36:51]
	v_exp_f32_e32 v136, v136
	v_exp_f32_e32 v137, v137
	ds_read_b64_tr_b16 v[88:89], v69 offset:30720
	ds_read_b64_tr_b16 v[90:91], v69 offset:31232
	s_waitcnt lgkmcnt(6)
	v_mfma_f32_32x32x16_bf16 v[36:51], v[148:151], v[84:87], v[36:51]
	v_exp_f32_e32 v138, v138
	v_exp_f32_e32 v139, v139
	ds_read_b64_tr_b16 v[84:85], v69 offset:31744
	ds_read_b64_tr_b16 v[86:87], v69 offset:32256
	s_waitcnt lgkmcnt(6)
	v_mfma_f32_32x32x16_bf16 v[52:67], v[160:163], v[76:79], v[52:67]
	v_exp_f32_e32 v140, v140
	v_exp_f32_e32 v141, v141
	ds_read_b64_tr_b16 v[76:77], v69 offset:32768
	ds_read_b64_tr_b16 v[78:79], v69 offset:33280
	s_waitcnt lgkmcnt(6)
	v_mfma_f32_32x32x16_bf16 v[52:67], v[156:159], v[80:83], v[52:67]
	v_exp_f32_e32 v142, v142
	v_exp_f32_e32 v143, v143
	ds_read_b64_tr_b16 v[80:81], v69 offset:33792
	ds_read_b64_tr_b16 v[82:83], v69 offset:34304
	s_waitcnt lgkmcnt(6)
	v_mfma_f32_32x32x16_bf16 v[52:67], v[152:155], v[88:91], v[52:67]
	v_exp_f32_e32 v144, v144
	v_exp_f32_e32 v145, v145
	ds_read_b64_tr_b16 v[88:89], v69 offset:34816
	ds_read_b64_tr_b16 v[90:91], v69 offset:35328
	s_waitcnt lgkmcnt(6)
	v_mfma_f32_32x32x16_bf16 v[52:67], v[148:151], v[84:87], v[52:67]
	v_exp_f32_e32 v146, v146
	v_exp_f32_e32 v147, v147
	ds_read_b64_tr_b16 v[84:85], v69 offset:35840
	ds_read_b64_tr_b16 v[86:87], v69 offset:36352
	s_waitcnt lgkmcnt(6)
	v_mfma_f32_32x32x16_bf16 v[4:19], v[160:163], v[76:79], v[4:19]
	v_exp_f32_e32 v116, v116
	v_exp_f32_e32 v117, v117
	ds_read_b64_tr_b16 v[76:77], v69 offset:36864
	ds_read_b64_tr_b16 v[78:79], v69 offset:37376
	s_waitcnt lgkmcnt(6)
	v_mfma_f32_32x32x16_bf16 v[4:19], v[156:159], v[80:83], v[4:19]
	v_exp_f32_e32 v118, v118
	v_exp_f32_e32 v119, v119
	ds_read_b64_tr_b16 v[80:81], v69 offset:37888
	ds_read_b64_tr_b16 v[82:83], v69 offset:38400
	s_waitcnt lgkmcnt(6)
	v_mfma_f32_32x32x16_bf16 v[4:19], v[152:155], v[88:91], v[4:19]
	v_exp_f32_e32 v120, v120
	v_exp_f32_e32 v121, v121
	ds_read_b64_tr_b16 v[88:89], v69 offset:38912
	ds_read_b64_tr_b16 v[90:91], v69 offset:39424
	s_waitcnt lgkmcnt(6)
	v_mfma_f32_32x32x16_bf16 v[4:19], v[148:151], v[84:87], v[4:19]
	v_exp_f32_e32 v122, v122
	v_exp_f32_e32 v123, v123
	ds_read_b64_tr_b16 v[84:85], v69 offset:39936
	ds_read_b64_tr_b16 v[86:87], v69 offset:40448
	v_add_u32_e32 v69, s16, v230
	ds_read_b128 v[92:95], v69
	ds_read_b128 v[96:99], v69 offset:512
	s_waitcnt lgkmcnt(8)
	v_mfma_f32_32x32x16_bf16 v[20:35], v[160:163], v[76:79], v[20:35]
	v_exp_f32_e32 v124, v124
	v_exp_f32_e32 v125, v125
	ds_read_b128 v[76:79], v69 offset:2048
	ds_read_b128 v[180:183], v69 offset:2560
	s_waitcnt lgkmcnt(8)
	v_mfma_f32_32x32x16_bf16 v[20:35], v[156:159], v[80:83], v[20:35]
	v_exp_f32_e32 v126, v126
	v_exp_f32_e32 v127, v127
	ds_read_b128 v[80:83], v69 offset:4096
	ds_read_b128 v[184:187], v69 offset:4608
	ds_read_b128 v[188:191], v69 offset:6144
	ds_read_b128 v[192:195], v69 offset:6656
	s_waitcnt lgkmcnt(10)
	v_mfma_f32_32x32x16_bf16 v[20:35], v[152:155], v[88:91], v[20:35]
	v_exp_f32_e32 v128, v128
	v_exp_f32_e32 v129, v129
	s_waitcnt lgkmcnt(8)
	v_mfma_f32_32x32x16_bf16 v[20:35], v[148:151], v[84:87], v[20:35]
	v_exp_f32_e32 v130, v130
	v_exp_f32_e32 v131, v131
	s_add_i32 s17, s26, 0x2000
	s_cmpk_lg_i32 s26, 0x4000
	s_cselect_b32 s24, s17, 0
	v_lshl_add_u32 v69, s3, 1, v232
	s_waitcnt vmcnt(3) lgkmcnt(0)
	s_barrier
	ds_read_b64_tr_b16 v[196:197], v69 offset:24576
	ds_read_b64_tr_b16 v[198:199], v69 offset:25088
	s_waitcnt lgkmcnt(9)
	v_mfma_f32_32x32x16_bf16 v[100:115], v[92:95], v[176:179], 0
	v_add_f32_e32 v84, v132, v133
	v_add_f32_e32 v84, v134, v84
	v_add_f32_e32 v84, v135, v84
	v_add_f32_e32 v84, v136, v84
	v_add_f32_e32 v84, v137, v84
	v_cvt_pk_bf16_f32 v160, v132, v133
	v_cvt_pk_bf16_f32 v161, v134, v135
	v_add_f32_e32 v84, v138, v84
	v_add_f32_e32 v84, v139, v84
	v_add_f32_e32 v84, v140, v84
	v_add_f32_e32 v148, v141, v84
	s_waitcnt lgkmcnt(8)
	v_mfma_f32_32x32x16_bf16 v[84:99], v[96:99], v[176:179], 0
	v_cvt_pk_bf16_f32 v162, v136, v137
	v_cvt_pk_bf16_f32 v163, v138, v139
	ds_read_b64_tr_b16 v[132:133], v69 offset:25600
	ds_read_b64_tr_b16 v[134:135], v69 offset:26112
	s_waitcnt lgkmcnt(9)
	v_mfma_f32_32x32x16_bf16 v[100:115], v[76:79], v[172:175], v[100:115]
	v_add_f32_e32 v76, v142, v148
	v_add_f32_e32 v76, v143, v76
	v_add_f32_e32 v76, v144, v76
	v_add_f32_e32 v76, v145, v76
	v_cvt_pk_bf16_f32 v156, v140, v141
	v_cvt_pk_bf16_f32 v157, v142, v143
	s_waitcnt lgkmcnt(8)
	v_mfma_f32_32x32x16_bf16 v[84:99], v[180:183], v[172:175], v[84:99]
	v_add_f32_e32 v76, v146, v76
	v_add_f32_e32 v76, v147, v76
	v_add_f32_e32 v76, v116, v76
	v_add_f32_e32 v136, v117, v76
	v_cvt_pk_bf16_f32 v158, v144, v145
	v_cvt_pk_bf16_f32 v159, v146, v147
	ds_read_b64_tr_b16 v[76:77], v69 offset:26624
	ds_read_b64_tr_b16 v[78:79], v69 offset:27136
	s_waitcnt lgkmcnt(9)
	v_mfma_f32_32x32x16_bf16 v[100:115], v[80:83], v[168:171], v[100:115]
	v_add_f32_e32 v80, v118, v136
	v_add_f32_e32 v80, v119, v80
	v_add_f32_e32 v80, v120, v80
	v_add_f32_e32 v80, v121, v80
	v_cvt_pk_bf16_f32 v152, v116, v117
	v_cvt_pk_bf16_f32 v153, v118, v119
	s_waitcnt lgkmcnt(8)
	v_mfma_f32_32x32x16_bf16 v[84:99], v[184:187], v[168:171], v[84:99]
	v_add_f32_e32 v80, v122, v80
	v_add_f32_e32 v80, v123, v80
	v_add_f32_e32 v80, v124, v80
	v_add_f32_e32 v116, v125, v80
	v_cvt_pk_bf16_f32 v154, v120, v121
	v_cvt_pk_bf16_f32 v155, v122, v123
	ds_read_b64_tr_b16 v[80:81], v69 offset:27648
	ds_read_b64_tr_b16 v[82:83], v69 offset:28160
	s_waitcnt lgkmcnt(9)
	v_mfma_f32_32x32x16_bf16 v[100:115], v[188:191], v[164:167], v[100:115]
	v_add_f32_e32 v116, v126, v116
	v_add_f32_e32 v116, v127, v116
	v_add_f32_e32 v116, v128, v116
	v_add_f32_e32 v116, v129, v116
	v_cvt_pk_bf16_f32 v148, v124, v125
	v_cvt_pk_bf16_f32 v149, v126, v127
	s_waitcnt lgkmcnt(8)
	v_mfma_f32_32x32x16_bf16 v[84:99], v[192:195], v[164:167], v[84:99]
	v_add_f32_e32 v116, v130, v116
	v_add_f32_e32 v116, v131, v116
	v_add_f32_e32 v116, 0, v116
	v_cvt_pk_bf16_f32 v150, v128, v129
	v_cvt_pk_bf16_f32 v151, v130, v131
	s_add_i32 m0, s26, s0
	v_lshl_add_u64 v[74:75], v[74:75], 0, s[28:29]
	global_load_lds_dwordx4 v[74:75], off
	s_lshl_b32 s3, s24, 1
	s_add_i32 s3, s3, s1
	s_mov_b32 m0, s3
	v_lshl_add_u64 v[74:75], v[72:73], 0, s[66:67]
	global_load_lds_dwordx4 v[74:75], off
	s_add_i32 m0, s3, 0x2000
	v_lshl_add_u64 v[72:73], v[72:73], 0, s[72:73]
	global_load_lds_dwordx4 v[72:73], off
	v_add_f32_e32 v68, v68, v116
	s_waitcnt lgkmcnt(6)
	v_mfma_f32_32x32x16_bf16 v[36:51], v[160:163], v[196:199], v[36:51]
	v_exp_f32_e32 v100, v100
	v_exp_f32_e32 v101, v101
	ds_read_b64_tr_b16 v[72:73], v69 offset:28672
	ds_read_b64_tr_b16 v[74:75], v69 offset:29184
	s_waitcnt lgkmcnt(6)
	v_mfma_f32_32x32x16_bf16 v[36:51], v[156:159], v[132:135], v[36:51]
	v_exp_f32_e32 v102, v102
	v_exp_f32_e32 v103, v103
	ds_read_b64_tr_b16 v[116:117], v69 offset:29696
	ds_read_b64_tr_b16 v[118:119], v69 offset:30208
	s_waitcnt lgkmcnt(6)
	v_mfma_f32_32x32x16_bf16 v[36:51], v[152:155], v[76:79], v[36:51]
	v_exp_f32_e32 v104, v104
	v_exp_f32_e32 v105, v105
	ds_read_b64_tr_b16 v[76:77], v69 offset:30720
	ds_read_b64_tr_b16 v[78:79], v69 offset:31232
	s_waitcnt lgkmcnt(6)
	v_mfma_f32_32x32x16_bf16 v[36:51], v[148:151], v[80:83], v[36:51]
	v_exp_f32_e32 v106, v106
	v_exp_f32_e32 v107, v107
	ds_read_b64_tr_b16 v[80:81], v69 offset:31744
	ds_read_b64_tr_b16 v[82:83], v69 offset:32256
	s_waitcnt lgkmcnt(6)
	v_mfma_f32_32x32x16_bf16 v[52:67], v[160:163], v[72:75], v[52:67]
	v_exp_f32_e32 v108, v108
	v_exp_f32_e32 v109, v109
	ds_read_b64_tr_b16 v[72:73], v69 offset:32768
	ds_read_b64_tr_b16 v[74:75], v69 offset:33280
	s_waitcnt lgkmcnt(6)
	v_mfma_f32_32x32x16_bf16 v[52:67], v[156:159], v[116:119], v[52:67]
	v_exp_f32_e32 v110, v110
	v_exp_f32_e32 v111, v111
	ds_read_b64_tr_b16 v[116:117], v69 offset:33792
	ds_read_b64_tr_b16 v[118:119], v69 offset:34304
	s_waitcnt lgkmcnt(6)
	v_mfma_f32_32x32x16_bf16 v[52:67], v[152:155], v[76:79], v[52:67]
	v_exp_f32_e32 v112, v112
	v_exp_f32_e32 v113, v113
	ds_read_b64_tr_b16 v[76:77], v69 offset:34816
	ds_read_b64_tr_b16 v[78:79], v69 offset:35328
	s_waitcnt lgkmcnt(6)
	v_mfma_f32_32x32x16_bf16 v[52:67], v[148:151], v[80:83], v[52:67]
	v_exp_f32_e32 v114, v114
	v_exp_f32_e32 v115, v115
	ds_read_b64_tr_b16 v[80:81], v69 offset:35840
	ds_read_b64_tr_b16 v[82:83], v69 offset:36352
	s_waitcnt lgkmcnt(6)
	v_mfma_f32_32x32x16_bf16 v[4:19], v[160:163], v[72:75], v[4:19]
	v_exp_f32_e32 v84, v84
	v_exp_f32_e32 v85, v85
	ds_read_b64_tr_b16 v[72:73], v69 offset:36864
	ds_read_b64_tr_b16 v[74:75], v69 offset:37376
	s_waitcnt lgkmcnt(6)
	v_mfma_f32_32x32x16_bf16 v[4:19], v[156:159], v[116:119], v[4:19]
	v_exp_f32_e32 v86, v86
	v_exp_f32_e32 v87, v87
	ds_read_b64_tr_b16 v[116:117], v69 offset:37888
	ds_read_b64_tr_b16 v[118:119], v69 offset:38400
	s_waitcnt lgkmcnt(6)
	v_mfma_f32_32x32x16_bf16 v[4:19], v[152:155], v[76:79], v[4:19]
	v_exp_f32_e32 v88, v88
	v_exp_f32_e32 v89, v89
	ds_read_b64_tr_b16 v[76:77], v69 offset:38912
	ds_read_b64_tr_b16 v[78:79], v69 offset:39424
	s_waitcnt lgkmcnt(6)
	v_mfma_f32_32x32x16_bf16 v[4:19], v[148:151], v[80:83], v[4:19]
	v_exp_f32_e32 v90, v90
	v_exp_f32_e32 v91, v91
	ds_read_b64_tr_b16 v[80:81], v69 offset:39936
	ds_read_b64_tr_b16 v[82:83], v69 offset:40448
	v_add_u32_e32 v69, s24, v230
	ds_read_b128 v[208:211], v69
	ds_read_b128 v[200:203], v69 offset:512
	s_waitcnt lgkmcnt(8)
	v_mfma_f32_32x32x16_bf16 v[20:35], v[160:163], v[72:75], v[20:35]
	v_exp_f32_e32 v92, v92
	v_exp_f32_e32 v93, v93
	ds_read_b128 v[204:207], v69 offset:2048
	ds_read_b128 v[196:199], v69 offset:2560
	s_waitcnt lgkmcnt(8)
	v_mfma_f32_32x32x16_bf16 v[20:35], v[156:159], v[116:119], v[20:35]
	v_exp_f32_e32 v94, v94
	v_exp_f32_e32 v95, v95
	ds_read_b128 v[192:195], v69 offset:4096
	ds_read_b128 v[188:191], v69 offset:4608
	ds_read_b128 v[184:187], v69 offset:6144
	ds_read_b128 v[180:183], v69 offset:6656
	s_waitcnt lgkmcnt(10)
	v_mfma_f32_32x32x16_bf16 v[20:35], v[152:155], v[76:79], v[20:35]
	v_exp_f32_e32 v96, v96
	v_exp_f32_e32 v97, v97
	s_waitcnt lgkmcnt(8)
	v_mfma_f32_32x32x16_bf16 v[20:35], v[148:151], v[80:83], v[20:35]
	v_exp_f32_e32 v98, v98
	v_exp_f32_e32 v99, v99
	s_add_i32 s3, s24, 0x2000
	s_cmpk_lg_i32 s24, 0x4000
	s_cselect_b32 s26, s3, 0
	s_add_i32 s18, s2, 2
	s_add_u32 s14, s14, 0x20000
	s_addc_u32 s15, s15, 0
	s_mov_b32 s17, s16
	s_cmp_ge_u32 s18, s21
	s_waitcnt vmcnt(3) lgkmcnt(0)
	s_barrier
	s_cbranch_scc0 .LBB0_413
	s_add_i32 s64, s2, -3
	s_lshl_b64 s[12:13], s[12:13], 9
	s_add_i32 s2, s64, 1
	s_cmp_lt_u32 s2, s21
	s_cbranch_scc0 .LBB0_441
